# P4a rope epilogue: rope table staged once per tile into the idle LDS staging slot, groups read it with ds_read_b128 (was eight serial global round trips per rope tile); on top of v174
# speedup vs baseline: 1.0080x; 1.0028x over previous
;     __device__ bool next(int i, Unit& u) const { return map((long)i * G + c, u); }
; template <class Epi, class Sched, bool ALIGN_EPI = true, bool SP2 = true>
; __device__ __forceinline__ void gemm_phase(LAS unsigned char* lds, const Gemm g, const Sched& S, const Epi& E) {
;     ...
;         const bool has_next = S.next(ui + 1, nxt);
;         const char* nA = has_next ? (const char*)g.A + (size_t)nxt.pm * tstep : cA; const char* nB = has_next ? (const char*)g.Bt + (size_t)nxt.pn * tstep : cB;
;     ...
;         for (int a = 0; a < 2; ++a)
; #pragma unroll
;             for (int b = 0; b < 2; ++b)
; #pragma unroll
;                 for (int m = 0; m < 4; ++m)
; #pragma unroll
;                     for (int n = 0; n < 2; ++n) acc[a][b][m][n] = (f32x4){0.f, 0.f, 0.f, 0.f};
.LBB0_546:
	s_ashr_i32 s89, s88, 31
	s_lshl_b64 s[10:11], s[88:89], 19
	s_add_u32 s90, s97, s10
	s_addc_u32 s91, s3, s11
	s_and_b64 s[10:11], s[4:5], exec
	s_cselect_b32 s7, s91, s15
	s_cselect_b32 s9, s90, s14
	s_ashr_i32 s79, s78, 31
	s_lshl_b64 s[10:11], s[78:79], 19
	s_add_u32 s92, s86, s10
	s_addc_u32 s93, s87, s11
	s_and_b64 s[10:11], s[4:5], exec
	s_cselect_b32 s64, s93, s13
	s_cselect_b32 s79, s92, s12
	s_add_u32 s10, s14, 0x40080
	s_addc_u32 s11, s15, 0
	s_add_u32 s85, s12, 0x100
	v_mov_b32_e32 v0, 0
	s_addc_u32 s89, s13, 0
	s_mov_b32 s94, -2
	v_mov_b32_e32 v1, v0
	s_barrier
	v_mov_b64_e32 v[2:3], 0
	v_mov_b64_e32 v[4:5], 0
	v_mov_b64_e32 v[6:7], 0
	v_mov_b64_e32 v[16:17], 0
	v_mov_b64_e32 v[18:19], 0
	v_mov_b64_e32 v[20:21], 0
	v_mov_b64_e32 v[22:23], 0
	v_mov_b64_e32 v[32:33], 0
	v_mov_b64_e32 v[34:35], 0
	v_mov_b64_e32 v[36:37], 0
	v_mov_b64_e32 v[38:39], 0
	v_mov_b64_e32 v[48:49], 0
	v_mov_b64_e32 v[50:51], 0
	v_mov_b64_e32 v[52:53], 0
	v_mov_b64_e32 v[54:55], 0
	v_mov_b64_e32 v[8:9], 0
	v_mov_b64_e32 v[10:11], 0
	v_mov_b64_e32 v[12:13], 0
	v_mov_b64_e32 v[14:15], 0
	v_mov_b64_e32 v[24:25], 0
	v_mov_b64_e32 v[26:27], 0
	v_mov_b64_e32 v[28:29], 0
	v_mov_b64_e32 v[30:31], 0
	v_mov_b64_e32 v[40:41], 0
	v_mov_b64_e32 v[42:43], 0
	v_mov_b64_e32 v[44:45], 0
	v_mov_b64_e32 v[46:47], 0
	v_mov_b64_e32 v[56:57], 0
	v_mov_b64_e32 v[58:59], 0
	v_mov_b64_e32 v[60:61], 0
	v_mov_b64_e32 v[62:63], 0
	v_mov_b64_e32 v[64:65], 0
	v_mov_b64_e32 v[66:67], 0
	v_mov_b64_e32 v[68:69], 0
	v_mov_b64_e32 v[70:71], 0
	v_mov_b64_e32 v[80:81], 0
	v_mov_b64_e32 v[82:83], 0
	v_mov_b64_e32 v[84:85], 0
	v_mov_b64_e32 v[86:87], 0
	v_mov_b64_e32 v[96:97], 0
	v_mov_b64_e32 v[98:99], 0
	v_mov_b64_e32 v[100:101], 0
	v_mov_b64_e32 v[102:103], 0
	v_mov_b64_e32 v[112:113], 0
	v_mov_b64_e32 v[114:115], 0
	v_mov_b64_e32 v[116:117], 0
	v_mov_b64_e32 v[118:119], 0
	v_mov_b64_e32 v[72:73], 0
	v_mov_b64_e32 v[74:75], 0
	v_mov_b64_e32 v[76:77], 0
	v_mov_b64_e32 v[78:79], 0
	v_mov_b64_e32 v[88:89], 0
	v_mov_b64_e32 v[90:91], 0
	v_mov_b64_e32 v[92:93], 0
	v_mov_b64_e32 v[94:95], 0
	v_mov_b64_e32 v[104:105], 0
	v_mov_b64_e32 v[106:107], 0
	v_mov_b64_e32 v[108:109], 0
	v_mov_b64_e32 v[110:111], 0
	v_mov_b64_e32 v[120:121], 0
	v_mov_b64_e32 v[122:123], 0
	v_mov_b64_e32 v[124:125], 0
	v_mov_b64_e32 v[126:127], 0

;     __device__ __forceinline__ void operator()(const Acc& acc, const Unit& u, int wr, int wc, int fr, int fq) const {
;     ...
;                 const int row = u.pm * BM + ai * HALF + wr * 64 + m * 16 + fr;
;                 const bool ctx = row >= ML;
;                 int t, kvrow;
;                 if (!ctx) { const int b = row >> 13; t = row & (SEQ - 1); kvrow = b * NKV + CTXL + t; }
;                 else { const int rc = row - ML, b = rc >> 8; t = rc & (CTXL - 1); kvrow = b * NKV + t; }
;                 if (pn < 8) {
;                     const int hh = wc >> 1, mm = wc & 1, axis = fq >> 1, f0 = 8 * (fq & 1);
;                     const int col = (2 * (pn & 3) + hh) * 128 + mm * 64 + axis * 32 + f0;
;                     f32x4 x0a = acc[ai][0][m][0], x0b = acc[ai][0][m][1], x1a = acc[ai][1][m][0], x1b = acc[ai][1][m][1];
;                     if (pn < 4) { constexpr float QS = 0.125f * 1.4426950408889634f; x0a = x0a * QS; x0b = x0b * QS; x1a = x1a * QS; x1b = x1b * QS; }
;                     if (!ctx) {
;                         const int pos = axis ? (t & 63) : (t >> 6);
;                         const f32x4* rp = (const f32x4*)(rope + pos * 16 + f0);
;                         const f32x4 c01 = rp[0], c23 = rp[1], c45 = rp[2], c67 = rp[3];
;                         f32x4 o0a, o0b, o1a, o1b;
;                         o0a[0] = x0a[0] * c01[0] - x1a[0] * c01[1]; o1a[0] = x1a[0] * c01[0] + x0a[0] * c01[1];
;                         o0a[1] = x0a[1] * c01[2] - x1a[1] * c01[3]; o1a[1] = x1a[1] * c01[2] + x0a[1] * c01[3];
;                         o0a[2] = x0a[2] * c23[0] - x1a[2] * c23[1]; o1a[2] = x1a[2] * c23[0] + x0a[2] * c23[1];
;                         o0a[3] = x0a[3] * c23[2] - x1a[3] * c23[3]; o1a[3] = x1a[3] * c23[2] + x0a[3] * c23[3];
;                         o0b[0] = x0b[0] * c45[0] - x1b[0] * c45[1]; o1b[0] = x1b[0] * c45[0] + x0b[0] * c45[1];
;                         o0b[1] = x0b[1] * c45[2] - x1b[1] * c45[3]; o1b[1] = x1b[1] * c45[2] + x0b[1] * c45[3];
;                         o0b[2] = x0b[2] * c67[0] - x1b[2] * c67[1]; o1b[2] = x1b[2] * c67[0] + x0b[2] * c67[1];
;                         o0b[3] = x0b[3] * c67[2] - x1b[3] * c67[3]; o1b[3] = x1b[3] * c67[2] + x0b[3] * c67[3];
;                         x0a = o0a; x0b = o0b; x1a = o1a; x1b = o1b;
;                     }
.LBB0_550:
	v_mbcnt_lo_u32_b32 v194, -1, 0
	v_mbcnt_hi_u32_b32 v194, -1, v194
	v_readlane_b32 s98, v238, 40
	v_lshlrev_b32_e32 v194, 4, v194
	s_add_u32 s100, s30, 0x40000
	s_addc_u32 s101, s31, 0
	s_lshl_b32 s98, s98, 10
	s_add_i32 s99, s98, 0xc000
	v_add_u32_e32 v194, s98, v194
	s_mov_b32 m0, s99
	v_add_u32_e32 v195, 0x2000, v194
	global_load_lds_dwordx4 v194, s[100:101]
	s_add_i32 s99, s99, 0x2000
	s_mov_b32 m0, s99
	v_subrev_u32_e32 v196, s100, v140
	global_load_lds_dwordx4 v195, s[100:101]
	v_add_u32_e32 v196, 0xc000, v196
	s_waitcnt vmcnt(0)
	s_barrier
	s_lshl_b32 s79, s6, 8
	s_add_i32 s79, s79, s75
	s_cmp_gt_i32 s8, 7
	s_cselect_b64 s[94:95], -1, 0
	s_lshl_b32 s6, s8, 8
	s_add_i32 s64, s6, 0xfffff800
	s_cmp_lt_i32 s8, 4
	s_cselect_b64 s[6:7], -1, 0
	s_ashr_i32 s9, s79, 13
	s_mul_i32 s85, s9, 0x2100
	s_add_i32 s9, s79, 0xffffc000
	s_lshr_b32 s89, s9, 8
	s_mulk_i32 s89, 0x2100
	v_bitop3_b32 v136, s79, v159, v139 bitop3:0xc8
	v_or_b32_e32 v165, s79, v139
	s_addk_i32 s85, 0x100
	v_or_b32_e32 v150, s89, v136
	v_bitop3_b32 v136, s79, v163, v139 bitop3:0xc8
	v_add_u32_e32 v151, s85, v136
	v_cmp_lt_i32_e64 s[10:11], s19, v165
	v_cmp_gt_i32_e64 s[12:13], s47, v165
	s_mov_b64 s[14:15], -1
	v_cndmask_b32_e64 v152, v151, v150, s[10:11]
	s_and_b64 vcc, exec, s[94:95]
	v_lshlrev_b32_e32 v150, 1, v138
	s_cbranch_vccz .LBB0_552
	v_ashrrev_i32_e32 v153, 31, v152
	v_lshlrev_b64 v[166:167], 11, v[152:153]
	v_lshl_add_u64 v[166:167], s[62:63], 0, v[166:167]
	v_lshl_add_u64 v[166:167], s[64:65], 1, v[166:167]
	s_lshl_b32 s14, s48, 1
	s_mov_b32 s15, s65
	v_lshl_add_u64 v[166:167], v[166:167], 0, s[14:15]
	v_mov_b32_e32 v151, v137
	v_lshl_add_u64 v[170:171], v[166:167], 0, v[150:151]
	v_cvt_pk_bf16_f32 v166, v124, v125
	v_cvt_pk_bf16_f32 v167, v126, v127
	v_cvt_pk_bf16_f32 v168, v120, v121
	v_cvt_pk_bf16_f32 v169, v122, v123
	global_store_dwordx4 v[170:171], v[166:169], off
	s_mov_b64 s[14:15], 0
	s_nop 0
	v_cvt_pk_bf16_f32 v166, v116, v117
	v_cvt_pk_bf16_f32 v167, v118, v119
	v_cvt_pk_bf16_f32 v168, v112, v113
	v_cvt_pk_bf16_f32 v169, v114, v115
	global_store_dwordx4 v[170:171], v[166:169], off offset:256

;     __device__ __forceinline__ void operator()(const Acc& acc, const Unit& u, int wr, int wc, int fr, int fq) const {
;     ...
;                         const int pos = axis ? (t & 63) : (t >> 6);
;                         const f32x4* rp = (const f32x4*)(rope + pos * 16 + f0);
;                         const f32x4 c01 = rp[0], c23 = rp[1], c45 = rp[2], c67 = rp[3];
;                         f32x4 o0a, o0b, o1a, o1b;
;                         o0a[0] = x0a[0] * c01[0] - x1a[0] * c01[1]; o1a[0] = x1a[0] * c01[0] + x0a[0] * c01[1];
;                         o0a[1] = x0a[1] * c01[2] - x1a[1] * c01[3]; o1a[1] = x1a[1] * c01[2] + x0a[1] * c01[3];
;                         o0a[2] = x0a[2] * c23[0] - x1a[2] * c23[1]; o1a[2] = x1a[2] * c23[0] + x0a[2] * c23[1];
;                         o0a[3] = x0a[3] * c23[2] - x1a[3] * c23[3]; o1a[3] = x1a[3] * c23[2] + x0a[3] * c23[3];
;                         o0b[0] = x0b[0] * c45[0] - x1b[0] * c45[1]; o1b[0] = x1b[0] * c45[0] + x0b[0] * c45[1];
;                         o0b[1] = x0b[1] * c45[2] - x1b[1] * c45[3]; o1b[1] = x1b[1] * c45[2] + x0b[1] * c45[3];
;                         o0b[2] = x0b[2] * c67[0] - x1b[2] * c67[1]; o1b[2] = x1b[2] * c67[0] + x0b[2] * c67[1];
;                         o0b[3] = x0b[3] * c67[2] - x1b[3] * c67[3]; o1b[3] = x1b[3] * c67[2] + x0b[3] * c67[3];
;                         x0a = o0a; x0b = o0b; x1a = o1a; x1b = o1b;
.LBB0_555:
	s_and_saveexec_b64 s[14:15], s[12:13]
	s_cbranch_execz .LBB0_557
	v_lshrrev_b32_e32 v136, 6, v136
	v_cndmask_b32_e64 v136, v139, v136, s[0:1]
	v_lshlrev_b32_e32 v136, 7, v136
	v_lshl_add_u64 v[180:181], v[140:141], 0, v[136:137]
	v_add_u32_e32 v197, v196, v136
	ds_read_b128 v[166:169], v197 offset:48
	ds_read_b128 v[170:173], v197 offset:32
	ds_read_b128 v[176:179], v197 offset:16
	ds_read_b128 v[180:183], v197
	s_waitcnt lgkmcnt(0)
	v_mul_f32_e32 v188, v118, v177
	v_mov_b32_e32 v185, v182
	v_mov_b32_e32 v182, v181
	v_mov_b32_e32 v184, v180
	v_pk_mul_f32 v[180:181], v[116:117], v[182:183]
	v_pk_mul_f32 v[186:187], v[124:125], v[182:183]
	v_mul_f32_e32 v182, v126, v176
	v_mul_f32_e32 v176, v118, v176
	v_mul_f32_e32 v190, v126, v177
	v_mov_b32_e32 v118, v127
	v_mov_b32_e32 v126, v119
	v_pk_mul_f32 v[192:193], v[118:119], v[178:179]
	v_pk_mul_f32 v[118:119], v[126:127], v[178:179]
	v_pk_fma_f32 v[180:181], v[124:125], v[184:185], v[180:181] neg_lo:[0,0,1] neg_hi:[0,0,1]
	v_mov_b32_e32 v177, v118
	v_mov_b32_e32 v191, v119
	v_pk_add_f32 v[118:119], v[176:177], v[190:191]
	v_mov_b32_e32 v177, v172
	v_mov_b32_e32 v172, v171
	v_mov_b32_e32 v176, v170
	v_pk_mul_f32 v[124:125], v[112:113], v[172:173]
	v_pk_mul_f32 v[170:171], v[120:121], v[172:173]
	v_mul_f32_e32 v126, v122, v166
	v_mul_f32_e32 v172, v114, v167
	v_mul_f32_e32 v166, v114, v166
	v_mov_b32_e32 v114, v123
	v_pk_fma_f32 v[116:117], v[116:117], v[184:185], v[186:187]
	v_pk_mul_f32 v[184:185], v[114:115], v[168:169]
	v_mul_f32_e32 v178, v122, v167
	v_mov_b32_e32 v127, v184
	v_mov_b32_e32 v173, v185
	v_pk_fma_f32 v[124:125], v[120:121], v[176:177], v[124:125] neg_lo:[0,0,1] neg_hi:[0,0,1]
	v_mov_b32_e32 v122, v115
	v_mov_b32_e32 v183, v192
	v_mov_b32_e32 v189, v193
	v_pk_add_f32 v[126:127], v[126:127], v[172:173] neg_lo:[0,1] neg_hi:[0,1]
	v_pk_mul_f32 v[114:115], v[122:123], v[168:169]
	v_mov_b64_e32 v[120:121], v[124:125]
	v_pk_add_f32 v[182:183], v[182:183], v[188:189] neg_lo:[0,1] neg_hi:[0,1]
	v_mov_b32_e32 v167, v114
	v_mov_b32_e32 v179, v115
	v_mov_b64_e32 v[122:123], v[126:127]
	v_mov_b64_e32 v[124:125], v[180:181]
	v_pk_fma_f32 v[112:113], v[112:113], v[176:177], v[170:171]
	v_pk_add_f32 v[114:115], v[166:167], v[178:179]
	v_mov_b64_e32 v[126:127], v[182:183]

;     __device__ __forceinline__ void operator()(const Acc& acc, const Unit& u, int wr, int wc, int fr, int fq) const {
;     ...
;                         const int pos = axis ? (t & 63) : (t >> 6);
;                         const f32x4* rp = (const f32x4*)(rope + pos * 16 + f0);
;                         const f32x4 c01 = rp[0], c23 = rp[1], c45 = rp[2], c67 = rp[3];
;                         f32x4 o0a, o0b, o1a, o1b;
;                         o0a[0] = x0a[0] * c01[0] - x1a[0] * c01[1]; o1a[0] = x1a[0] * c01[0] + x0a[0] * c01[1];
;                         o0a[1] = x0a[1] * c01[2] - x1a[1] * c01[3]; o1a[1] = x1a[1] * c01[2] + x0a[1] * c01[3];
;                         o0a[2] = x0a[2] * c23[0] - x1a[2] * c23[1]; o1a[2] = x1a[2] * c23[0] + x0a[2] * c23[1];
;                         o0a[3] = x0a[3] * c23[2] - x1a[3] * c23[3]; o1a[3] = x1a[3] * c23[2] + x0a[3] * c23[3];
;                         o0b[0] = x0b[0] * c45[0] - x1b[0] * c45[1]; o1b[0] = x1b[0] * c45[0] + x0b[0] * c45[1];
;                         o0b[1] = x0b[1] * c45[2] - x1b[1] * c45[3]; o1b[1] = x1b[1] * c45[2] + x0b[1] * c45[3];
;                         o0b[2] = x0b[2] * c67[0] - x1b[2] * c67[1]; o1b[2] = x1b[2] * c67[0] + x0b[2] * c67[1];
;                         o0b[3] = x0b[3] * c67[2] - x1b[3] * c67[3]; o1b[3] = x1b[3] * c67[2] + x0b[3] * c67[3];
;                         x0a = o0a; x0b = o0b; x1a = o1a; x1b = o1b;
.LBB0_565:
	s_and_saveexec_b64 s[94:95], s[14:15]
	s_cbranch_execz .LBB0_567
	v_and_b32_e32 v113, 31, v114
	v_lshrrev_b32_e32 v115, 6, v115
	v_cndmask_b32_e64 v113, v113, v115, s[0:1]
	v_lshlrev_b32_e32 v136, 7, v113
	v_lshl_add_u64 v[166:167], v[140:141], 0, v[136:137]
	v_add_u32_e32 v197, v196, v136
	ds_read_b128 v[116:119], v197 offset:48
	ds_read_b128 v[120:123], v197 offset:32
	ds_read_b128 v[124:127], v197 offset:16
	ds_read_b128 v[166:169], v197
	s_waitcnt lgkmcnt(0)
	v_mul_f32_e32 v176, v102, v125
	v_mov_b32_e32 v171, v168
	v_mov_b32_e32 v168, v167
	v_mov_b32_e32 v170, v166
	v_pk_mul_f32 v[166:167], v[100:101], v[168:169]
	v_pk_mul_f32 v[172:173], v[108:109], v[168:169]
	v_mul_f32_e32 v168, v110, v124
	v_mul_f32_e32 v124, v102, v124
	v_mul_f32_e32 v178, v110, v125
	v_mov_b32_e32 v102, v111
	v_mov_b32_e32 v110, v103
	v_pk_mul_f32 v[180:181], v[102:103], v[126:127]
	v_pk_mul_f32 v[102:103], v[110:111], v[126:127]
	v_pk_fma_f32 v[166:167], v[108:109], v[170:171], v[166:167] neg_lo:[0,0,1] neg_hi:[0,0,1]
	v_mov_b32_e32 v125, v102
	v_mov_b32_e32 v179, v103
	v_pk_add_f32 v[102:103], v[124:125], v[178:179]
	v_mov_b32_e32 v125, v122
	v_mov_b32_e32 v122, v121
	v_mov_b32_e32 v124, v120
	v_pk_mul_f32 v[108:109], v[96:97], v[122:123]
	v_pk_mul_f32 v[120:121], v[104:105], v[122:123]
	v_mul_f32_e32 v110, v106, v116
	v_mul_f32_e32 v122, v98, v117
	v_mul_f32_e32 v116, v98, v116
	v_mov_b32_e32 v98, v107
	v_pk_fma_f32 v[100:101], v[100:101], v[170:171], v[172:173]
	v_pk_mul_f32 v[170:171], v[98:99], v[118:119]
	v_mul_f32_e32 v126, v106, v117
	v_mov_b32_e32 v111, v170
	v_mov_b32_e32 v123, v171
	v_pk_fma_f32 v[108:109], v[104:105], v[124:125], v[108:109] neg_lo:[0,0,1] neg_hi:[0,0,1]
	v_mov_b32_e32 v106, v99
	v_mov_b32_e32 v169, v180
	v_mov_b32_e32 v177, v181
	v_pk_add_f32 v[110:111], v[110:111], v[122:123] neg_lo:[0,1] neg_hi:[0,1]
	v_pk_mul_f32 v[98:99], v[106:107], v[118:119]
	v_mov_b64_e32 v[104:105], v[108:109]
	v_pk_add_f32 v[168:169], v[168:169], v[176:177] neg_lo:[0,1] neg_hi:[0,1]
	v_mov_b32_e32 v117, v98
	v_mov_b32_e32 v127, v99
	v_mov_b64_e32 v[106:107], v[110:111]
	v_mov_b64_e32 v[108:109], v[166:167]
	v_pk_fma_f32 v[96:97], v[96:97], v[124:125], v[120:121]
	v_pk_add_f32 v[98:99], v[116:117], v[126:127]
	v_mov_b64_e32 v[110:111], v[168:169]

;     __device__ __forceinline__ void operator()(const Acc& acc, const Unit& u, int wr, int wc, int fr, int fq) const {
;     ...
;                         const int pos = axis ? (t & 63) : (t >> 6);
;                         const f32x4* rp = (const f32x4*)(rope + pos * 16 + f0);
;                         const f32x4 c01 = rp[0], c23 = rp[1], c45 = rp[2], c67 = rp[3];
;                         f32x4 o0a, o0b, o1a, o1b;
;                         o0a[0] = x0a[0] * c01[0] - x1a[0] * c01[1]; o1a[0] = x1a[0] * c01[0] + x0a[0] * c01[1];
;                         o0a[1] = x0a[1] * c01[2] - x1a[1] * c01[3]; o1a[1] = x1a[1] * c01[2] + x0a[1] * c01[3];
;                         o0a[2] = x0a[2] * c23[0] - x1a[2] * c23[1]; o1a[2] = x1a[2] * c23[0] + x0a[2] * c23[1];
;                         o0a[3] = x0a[3] * c23[2] - x1a[3] * c23[3]; o1a[3] = x1a[3] * c23[2] + x0a[3] * c23[3];
;                         o0b[0] = x0b[0] * c45[0] - x1b[0] * c45[1]; o1b[0] = x1b[0] * c45[0] + x0b[0] * c45[1];
;                         o0b[1] = x0b[1] * c45[2] - x1b[1] * c45[3]; o1b[1] = x1b[1] * c45[2] + x0b[1] * c45[3];
;                         o0b[2] = x0b[2] * c67[0] - x1b[2] * c67[1]; o1b[2] = x1b[2] * c67[0] + x0b[2] * c67[1];
;                         o0b[3] = x0b[3] * c67[2] - x1b[3] * c67[3]; o1b[3] = x1b[3] * c67[2] + x0b[3] * c67[3];
;                         x0a = o0a; x0b = o0b; x1a = o1a; x1b = o1b;
.LBB0_575:
	s_and_saveexec_b64 s[94:95], s[14:15]
	s_cbranch_execz .LBB0_577
	v_and_b32_e32 v97, 47, v98
	v_lshrrev_b32_e32 v99, 6, v99
	v_cndmask_b32_e64 v97, v97, v99, s[0:1]
	v_lshlrev_b32_e32 v136, 7, v97
	v_lshl_add_u64 v[112:113], v[140:141], 0, v[136:137]
	v_add_u32_e32 v197, v196, v136
	ds_read_b128 v[100:103], v197 offset:48
	ds_read_b128 v[104:107], v197 offset:32
	ds_read_b128 v[108:111], v197 offset:16
	ds_read_b128 v[112:115], v197
	s_waitcnt lgkmcnt(0)
	v_mul_f32_e32 v120, v86, v109
	v_mov_b32_e32 v117, v114
	v_mov_b32_e32 v114, v113
	v_mov_b32_e32 v116, v112
	v_pk_mul_f32 v[112:113], v[84:85], v[114:115]
	v_pk_mul_f32 v[118:119], v[92:93], v[114:115]
	v_mul_f32_e32 v114, v94, v108
	v_mul_f32_e32 v108, v86, v108
	v_mul_f32_e32 v122, v94, v109
	v_mov_b32_e32 v86, v95
	v_mov_b32_e32 v94, v87
	v_pk_mul_f32 v[124:125], v[86:87], v[110:111]
	v_pk_mul_f32 v[86:87], v[94:95], v[110:111]
	v_pk_fma_f32 v[112:113], v[92:93], v[116:117], v[112:113] neg_lo:[0,0,1] neg_hi:[0,0,1]
	v_mov_b32_e32 v109, v86
	v_mov_b32_e32 v123, v87
	v_pk_add_f32 v[86:87], v[108:109], v[122:123]
	v_mov_b32_e32 v109, v106
	v_mov_b32_e32 v106, v105
	v_mov_b32_e32 v108, v104
	v_pk_mul_f32 v[92:93], v[80:81], v[106:107]
	v_pk_mul_f32 v[104:105], v[88:89], v[106:107]
	v_mul_f32_e32 v94, v90, v100
	v_mul_f32_e32 v106, v82, v101
	v_mul_f32_e32 v100, v82, v100
	v_mov_b32_e32 v82, v91
	v_pk_fma_f32 v[84:85], v[84:85], v[116:117], v[118:119]
	v_pk_mul_f32 v[116:117], v[82:83], v[102:103]
	v_mul_f32_e32 v110, v90, v101
	v_mov_b32_e32 v95, v116
	v_mov_b32_e32 v107, v117
	v_pk_fma_f32 v[92:93], v[88:89], v[108:109], v[92:93] neg_lo:[0,0,1] neg_hi:[0,0,1]
	v_mov_b32_e32 v90, v83
	v_mov_b32_e32 v115, v124
	v_mov_b32_e32 v121, v125
	v_pk_add_f32 v[94:95], v[94:95], v[106:107] neg_lo:[0,1] neg_hi:[0,1]
	v_pk_mul_f32 v[82:83], v[90:91], v[102:103]
	v_mov_b64_e32 v[88:89], v[92:93]
	v_pk_add_f32 v[114:115], v[114:115], v[120:121] neg_lo:[0,1] neg_hi:[0,1]
	v_mov_b32_e32 v101, v82
	v_mov_b32_e32 v111, v83
	v_mov_b64_e32 v[90:91], v[94:95]
	v_mov_b64_e32 v[92:93], v[112:113]
	v_pk_fma_f32 v[80:81], v[80:81], v[108:109], v[104:105]
	v_pk_add_f32 v[82:83], v[100:101], v[110:111]
	v_mov_b64_e32 v[94:95], v[114:115]

;     __device__ __forceinline__ void operator()(const Acc& acc, const Unit& u, int wr, int wc, int fr, int fq) const {
;     ...
;                         const int pos = axis ? (t & 63) : (t >> 6);
;                         const f32x4* rp = (const f32x4*)(rope + pos * 16 + f0);
;                         const f32x4 c01 = rp[0], c23 = rp[1], c45 = rp[2], c67 = rp[3];
;                         f32x4 o0a, o0b, o1a, o1b;
;                         o0a[0] = x0a[0] * c01[0] - x1a[0] * c01[1]; o1a[0] = x1a[0] * c01[0] + x0a[0] * c01[1];
;                         o0a[1] = x0a[1] * c01[2] - x1a[1] * c01[3]; o1a[1] = x1a[1] * c01[2] + x0a[1] * c01[3];
;                         o0a[2] = x0a[2] * c23[0] - x1a[2] * c23[1]; o1a[2] = x1a[2] * c23[0] + x0a[2] * c23[1];
;                         o0a[3] = x0a[3] * c23[2] - x1a[3] * c23[3]; o1a[3] = x1a[3] * c23[2] + x0a[3] * c23[3];
;                         o0b[0] = x0b[0] * c45[0] - x1b[0] * c45[1]; o1b[0] = x1b[0] * c45[0] + x0b[0] * c45[1];
;                         o0b[1] = x0b[1] * c45[2] - x1b[1] * c45[3]; o1b[1] = x1b[1] * c45[2] + x0b[1] * c45[3];
;                         o0b[2] = x0b[2] * c67[0] - x1b[2] * c67[1]; o1b[2] = x1b[2] * c67[0] + x0b[2] * c67[1];
;                         o0b[3] = x0b[3] * c67[2] - x1b[3] * c67[3]; o1b[3] = x1b[3] * c67[2] + x0b[3] * c67[3];
;                         x0a = o0a; x0b = o0b; x1a = o1a; x1b = o1b;
.LBB0_585:
	s_and_saveexec_b64 s[94:95], s[14:15]
	s_cbranch_execz .LBB0_587
	v_and_b32_e32 v81, 63, v82
	v_lshrrev_b32_e32 v83, 6, v83
	v_cndmask_b32_e64 v81, v81, v83, s[0:1]
	v_lshlrev_b32_e32 v136, 7, v81
	v_lshl_add_u64 v[96:97], v[140:141], 0, v[136:137]
	v_add_u32_e32 v197, v196, v136
	ds_read_b128 v[84:87], v197 offset:48
	ds_read_b128 v[88:91], v197 offset:32
	ds_read_b128 v[92:95], v197 offset:16
	ds_read_b128 v[96:99], v197
	s_waitcnt lgkmcnt(0)
	v_mul_f32_e32 v104, v70, v93
	v_mov_b32_e32 v101, v98
	v_mov_b32_e32 v98, v97
	v_mov_b32_e32 v100, v96
	v_pk_mul_f32 v[96:97], v[68:69], v[98:99]
	v_pk_mul_f32 v[102:103], v[76:77], v[98:99]
	v_mul_f32_e32 v98, v78, v92
	v_mul_f32_e32 v92, v70, v92
	v_mul_f32_e32 v106, v78, v93
	v_mov_b32_e32 v70, v79
	v_mov_b32_e32 v78, v71
	v_pk_mul_f32 v[108:109], v[70:71], v[94:95]
	v_pk_mul_f32 v[70:71], v[78:79], v[94:95]
	v_pk_fma_f32 v[96:97], v[76:77], v[100:101], v[96:97] neg_lo:[0,0,1] neg_hi:[0,0,1]
	v_mov_b32_e32 v93, v70
	v_mov_b32_e32 v107, v71
	v_pk_add_f32 v[70:71], v[92:93], v[106:107]
	v_mov_b32_e32 v93, v90
	v_mov_b32_e32 v90, v89
	v_mov_b32_e32 v92, v88
	v_pk_mul_f32 v[76:77], v[64:65], v[90:91]
	v_pk_mul_f32 v[88:89], v[72:73], v[90:91]
	v_mul_f32_e32 v78, v74, v84
	v_mul_f32_e32 v90, v66, v85
	v_mul_f32_e32 v84, v66, v84
	v_mov_b32_e32 v66, v75
	v_pk_fma_f32 v[68:69], v[68:69], v[100:101], v[102:103]
	v_pk_mul_f32 v[100:101], v[66:67], v[86:87]
	v_mul_f32_e32 v94, v74, v85
	v_mov_b32_e32 v79, v100
	v_mov_b32_e32 v91, v101
	v_pk_fma_f32 v[76:77], v[72:73], v[92:93], v[76:77] neg_lo:[0,0,1] neg_hi:[0,0,1]
	v_mov_b32_e32 v74, v67
	v_mov_b32_e32 v99, v108
	v_mov_b32_e32 v105, v109
	v_pk_add_f32 v[78:79], v[78:79], v[90:91] neg_lo:[0,1] neg_hi:[0,1]
	v_pk_mul_f32 v[66:67], v[74:75], v[86:87]
	v_mov_b64_e32 v[72:73], v[76:77]
	v_pk_add_f32 v[98:99], v[98:99], v[104:105] neg_lo:[0,1] neg_hi:[0,1]
	v_mov_b32_e32 v85, v66
	v_mov_b32_e32 v95, v67
	v_mov_b64_e32 v[74:75], v[78:79]
	v_mov_b64_e32 v[76:77], v[96:97]
	v_pk_fma_f32 v[64:65], v[64:65], v[92:93], v[88:89]
	v_pk_add_f32 v[66:67], v[84:85], v[94:95]
	v_mov_b64_e32 v[78:79], v[98:99]

;     __device__ __forceinline__ void operator()(const Acc& acc, const Unit& u, int wr, int wc, int fr, int fq) const {
;     ...
;                         const int pos = axis ? (t & 63) : (t >> 6);
;                         const f32x4* rp = (const f32x4*)(rope + pos * 16 + f0);
;                         const f32x4 c01 = rp[0], c23 = rp[1], c45 = rp[2], c67 = rp[3];
;                         f32x4 o0a, o0b, o1a, o1b;
;                         o0a[0] = x0a[0] * c01[0] - x1a[0] * c01[1]; o1a[0] = x1a[0] * c01[0] + x0a[0] * c01[1];
;                         o0a[1] = x0a[1] * c01[2] - x1a[1] * c01[3]; o1a[1] = x1a[1] * c01[2] + x0a[1] * c01[3];
;                         o0a[2] = x0a[2] * c23[0] - x1a[2] * c23[1]; o1a[2] = x1a[2] * c23[0] + x0a[2] * c23[1];
;                         o0a[3] = x0a[3] * c23[2] - x1a[3] * c23[3]; o1a[3] = x1a[3] * c23[2] + x0a[3] * c23[3];
;                         o0b[0] = x0b[0] * c45[0] - x1b[0] * c45[1]; o1b[0] = x1b[0] * c45[0] + x0b[0] * c45[1];
;                         o0b[1] = x0b[1] * c45[2] - x1b[1] * c45[3]; o1b[1] = x1b[1] * c45[2] + x0b[1] * c45[3];
;                         o0b[2] = x0b[2] * c67[0] - x1b[2] * c67[1]; o1b[2] = x1b[2] * c67[0] + x0b[2] * c67[1];
;                         o0b[3] = x0b[3] * c67[2] - x1b[3] * c67[3]; o1b[3] = x1b[3] * c67[2] + x0b[3] * c67[3];
;                         x0a = o0a; x0b = o0b; x1a = o1a; x1b = o1b;
.LBB0_595:
	s_and_saveexec_b64 s[94:95], s[14:15]
	s_cbranch_execz .LBB0_597
	v_lshrrev_b32_e32 v65, 6, v67
	v_cndmask_b32_e64 v65, v139, v65, s[0:1]
	v_lshlrev_b32_e32 v136, 7, v65
	v_lshl_add_u64 v[80:81], v[140:141], 0, v[136:137]
	v_add_u32_e32 v197, v196, v136
	ds_read_b128 v[68:71], v197 offset:48
	ds_read_b128 v[72:75], v197 offset:32
	ds_read_b128 v[76:79], v197 offset:16
	ds_read_b128 v[80:83], v197
	s_waitcnt lgkmcnt(0)
	v_mul_f32_e32 v88, v54, v77
	v_mov_b32_e32 v85, v82
	v_mov_b32_e32 v82, v81
	v_mov_b32_e32 v84, v80
	v_pk_mul_f32 v[80:81], v[52:53], v[82:83]
	v_pk_mul_f32 v[86:87], v[60:61], v[82:83]
	v_mul_f32_e32 v82, v62, v76
	v_mul_f32_e32 v76, v54, v76
	v_mul_f32_e32 v90, v62, v77
	v_mov_b32_e32 v54, v63
	v_mov_b32_e32 v62, v55
	v_pk_mul_f32 v[92:93], v[54:55], v[78:79]
	v_pk_mul_f32 v[54:55], v[62:63], v[78:79]
	v_pk_fma_f32 v[80:81], v[60:61], v[84:85], v[80:81] neg_lo:[0,0,1] neg_hi:[0,0,1]
	v_mov_b32_e32 v77, v54
	v_mov_b32_e32 v91, v55
	v_pk_add_f32 v[54:55], v[76:77], v[90:91]
	v_mov_b32_e32 v77, v74
	v_mov_b32_e32 v74, v73
	v_mov_b32_e32 v76, v72
	v_pk_mul_f32 v[60:61], v[48:49], v[74:75]
	v_pk_mul_f32 v[72:73], v[56:57], v[74:75]
	v_mul_f32_e32 v62, v58, v68
	v_mul_f32_e32 v74, v50, v69
	v_mul_f32_e32 v68, v50, v68
	v_mov_b32_e32 v50, v59
	v_pk_fma_f32 v[52:53], v[52:53], v[84:85], v[86:87]
	v_pk_mul_f32 v[84:85], v[50:51], v[70:71]
	v_mul_f32_e32 v78, v58, v69
	v_mov_b32_e32 v63, v84
	v_mov_b32_e32 v75, v85
	v_pk_fma_f32 v[60:61], v[56:57], v[76:77], v[60:61] neg_lo:[0,0,1] neg_hi:[0,0,1]
	v_mov_b32_e32 v58, v51
	v_mov_b32_e32 v83, v92
	v_mov_b32_e32 v89, v93
	v_pk_add_f32 v[62:63], v[62:63], v[74:75] neg_lo:[0,1] neg_hi:[0,1]
	v_pk_mul_f32 v[50:51], v[58:59], v[70:71]
	v_mov_b64_e32 v[56:57], v[60:61]
	v_pk_add_f32 v[82:83], v[82:83], v[88:89] neg_lo:[0,1] neg_hi:[0,1]
	v_mov_b32_e32 v69, v50
	v_mov_b32_e32 v79, v51
	v_mov_b64_e32 v[58:59], v[62:63]
	v_mov_b64_e32 v[60:61], v[80:81]
	v_pk_fma_f32 v[48:49], v[48:49], v[76:77], v[72:73]
	v_pk_add_f32 v[50:51], v[68:69], v[78:79]
	v_mov_b64_e32 v[62:63], v[82:83]

;     __device__ __forceinline__ void operator()(const Acc& acc, const Unit& u, int wr, int wc, int fr, int fq) const {
;     ...
;                         const int pos = axis ? (t & 63) : (t >> 6);
;                         const f32x4* rp = (const f32x4*)(rope + pos * 16 + f0);
;                         const f32x4 c01 = rp[0], c23 = rp[1], c45 = rp[2], c67 = rp[3];
;                         f32x4 o0a, o0b, o1a, o1b;
;                         o0a[0] = x0a[0] * c01[0] - x1a[0] * c01[1]; o1a[0] = x1a[0] * c01[0] + x0a[0] * c01[1];
;                         o0a[1] = x0a[1] * c01[2] - x1a[1] * c01[3]; o1a[1] = x1a[1] * c01[2] + x0a[1] * c01[3];
;                         o0a[2] = x0a[2] * c23[0] - x1a[2] * c23[1]; o1a[2] = x1a[2] * c23[0] + x0a[2] * c23[1];
;                         o0a[3] = x0a[3] * c23[2] - x1a[3] * c23[3]; o1a[3] = x1a[3] * c23[2] + x0a[3] * c23[3];
;                         o0b[0] = x0b[0] * c45[0] - x1b[0] * c45[1]; o1b[0] = x1b[0] * c45[0] + x0b[0] * c45[1];
;                         o0b[1] = x0b[1] * c45[2] - x1b[1] * c45[3]; o1b[1] = x1b[1] * c45[2] + x0b[1] * c45[3];
;                         o0b[2] = x0b[2] * c67[0] - x1b[2] * c67[1]; o1b[2] = x1b[2] * c67[0] + x0b[2] * c67[1];
;                         o0b[3] = x0b[3] * c67[2] - x1b[3] * c67[3]; o1b[3] = x1b[3] * c67[2] + x0b[3] * c67[3];
;                         x0a = o0a; x0b = o0b; x1a = o1a; x1b = o1b;
.LBB0_605:
	s_and_saveexec_b64 s[94:95], s[14:15]
	s_cbranch_execz .LBB0_607
	v_and_b32_e32 v49, 31, v50
	v_lshrrev_b32_e32 v51, 6, v51
	v_cndmask_b32_e64 v49, v49, v51, s[0:1]
	v_lshlrev_b32_e32 v136, 7, v49
	v_lshl_add_u64 v[64:65], v[140:141], 0, v[136:137]
	v_add_u32_e32 v197, v196, v136
	ds_read_b128 v[52:55], v197 offset:48
	ds_read_b128 v[56:59], v197 offset:32
	ds_read_b128 v[60:63], v197 offset:16
	ds_read_b128 v[68:71], v197
	s_waitcnt lgkmcnt(0)
	v_mul_f32_e32 v74, v38, v61
	v_mov_b32_e32 v65, v70
	v_mov_b32_e32 v70, v69
	v_mov_b32_e32 v64, v68
	v_pk_mul_f32 v[68:69], v[36:37], v[70:71]
	v_pk_mul_f32 v[72:73], v[44:45], v[70:71]
	v_mul_f32_e32 v70, v46, v60
	v_mul_f32_e32 v60, v38, v60
	v_mul_f32_e32 v76, v46, v61
	v_mov_b32_e32 v38, v47
	v_mov_b32_e32 v46, v39
	v_pk_mul_f32 v[78:79], v[38:39], v[62:63]
	v_pk_mul_f32 v[38:39], v[46:47], v[62:63]
	v_pk_fma_f32 v[68:69], v[44:45], v[64:65], v[68:69] neg_lo:[0,0,1] neg_hi:[0,0,1]
	v_mov_b32_e32 v61, v38
	v_mov_b32_e32 v77, v39
	v_pk_add_f32 v[38:39], v[60:61], v[76:77]
	v_mov_b32_e32 v61, v58
	v_mov_b32_e32 v58, v57
	v_mov_b32_e32 v60, v56
	v_pk_mul_f32 v[44:45], v[32:33], v[58:59]
	v_pk_mul_f32 v[56:57], v[40:41], v[58:59]
	v_mul_f32_e32 v46, v42, v52
	v_mul_f32_e32 v58, v34, v53
	v_mul_f32_e32 v52, v34, v52
	v_mov_b32_e32 v34, v43
	v_pk_fma_f32 v[36:37], v[36:37], v[64:65], v[72:73]
	v_pk_mul_f32 v[64:65], v[34:35], v[54:55]
	v_mul_f32_e32 v62, v42, v53
	v_mov_b32_e32 v47, v64
	v_mov_b32_e32 v59, v65
	v_pk_fma_f32 v[44:45], v[40:41], v[60:61], v[44:45] neg_lo:[0,0,1] neg_hi:[0,0,1]
	v_mov_b32_e32 v42, v35
	v_mov_b32_e32 v71, v78
	v_mov_b32_e32 v75, v79
	v_pk_add_f32 v[46:47], v[46:47], v[58:59] neg_lo:[0,1] neg_hi:[0,1]
	v_pk_mul_f32 v[34:35], v[42:43], v[54:55]
	v_mov_b64_e32 v[40:41], v[44:45]
	v_pk_add_f32 v[70:71], v[70:71], v[74:75] neg_lo:[0,1] neg_hi:[0,1]
	v_mov_b32_e32 v53, v34
	v_mov_b32_e32 v63, v35
	v_mov_b64_e32 v[42:43], v[46:47]
	v_mov_b64_e32 v[44:45], v[68:69]
	v_pk_fma_f32 v[32:33], v[32:33], v[60:61], v[56:57]
	v_pk_add_f32 v[34:35], v[52:53], v[62:63]
	v_mov_b64_e32 v[46:47], v[70:71]

;     __device__ __forceinline__ void operator()(const Acc& acc, const Unit& u, int wr, int wc, int fr, int fq) const {
;     ...
;                         const int pos = axis ? (t & 63) : (t >> 6);
;                         const f32x4* rp = (const f32x4*)(rope + pos * 16 + f0);
;                         const f32x4 c01 = rp[0], c23 = rp[1], c45 = rp[2], c67 = rp[3];
;                         f32x4 o0a, o0b, o1a, o1b;
;                         o0a[0] = x0a[0] * c01[0] - x1a[0] * c01[1]; o1a[0] = x1a[0] * c01[0] + x0a[0] * c01[1];
;                         o0a[1] = x0a[1] * c01[2] - x1a[1] * c01[3]; o1a[1] = x1a[1] * c01[2] + x0a[1] * c01[3];
;                         o0a[2] = x0a[2] * c23[0] - x1a[2] * c23[1]; o1a[2] = x1a[2] * c23[0] + x0a[2] * c23[1];
;                         o0a[3] = x0a[3] * c23[2] - x1a[3] * c23[3]; o1a[3] = x1a[3] * c23[2] + x0a[3] * c23[3];
;                         o0b[0] = x0b[0] * c45[0] - x1b[0] * c45[1]; o1b[0] = x1b[0] * c45[0] + x0b[0] * c45[1];
;                         o0b[1] = x0b[1] * c45[2] - x1b[1] * c45[3]; o1b[1] = x1b[1] * c45[2] + x0b[1] * c45[3];
;                         o0b[2] = x0b[2] * c67[0] - x1b[2] * c67[1]; o1b[2] = x1b[2] * c67[0] + x0b[2] * c67[1];
;                         o0b[3] = x0b[3] * c67[2] - x1b[3] * c67[3]; o1b[3] = x1b[3] * c67[2] + x0b[3] * c67[3];
;                         x0a = o0a; x0b = o0b; x1a = o1a; x1b = o1b;
.LBB0_615:
	s_and_saveexec_b64 s[94:95], s[14:15]
	s_cbranch_execz .LBB0_617
	v_and_b32_e32 v33, 47, v34
	v_lshrrev_b32_e32 v35, 6, v35
	v_cndmask_b32_e64 v33, v33, v35, s[0:1]
	v_lshlrev_b32_e32 v136, 7, v33
	v_lshl_add_u64 v[48:49], v[140:141], 0, v[136:137]
	v_add_u32_e32 v197, v196, v136
	ds_read_b128 v[36:39], v197 offset:48
	ds_read_b128 v[40:43], v197 offset:32
	ds_read_b128 v[44:47], v197 offset:16
	ds_read_b128 v[48:51], v197
	s_waitcnt lgkmcnt(0)
	v_mul_f32_e32 v56, v22, v45
	v_mov_b32_e32 v53, v50
	v_mov_b32_e32 v50, v49
	v_mov_b32_e32 v52, v48
	v_pk_mul_f32 v[48:49], v[20:21], v[50:51]
	v_pk_mul_f32 v[54:55], v[28:29], v[50:51]
	v_mul_f32_e32 v50, v30, v44
	v_mul_f32_e32 v44, v22, v44
	v_mul_f32_e32 v58, v30, v45
	v_mov_b32_e32 v22, v31
	v_mov_b32_e32 v30, v23
	v_pk_mul_f32 v[60:61], v[22:23], v[46:47]
	v_pk_mul_f32 v[22:23], v[30:31], v[46:47]
	v_pk_fma_f32 v[48:49], v[28:29], v[52:53], v[48:49] neg_lo:[0,0,1] neg_hi:[0,0,1]
	v_mov_b32_e32 v45, v22
	v_mov_b32_e32 v59, v23
	v_pk_add_f32 v[22:23], v[44:45], v[58:59]
	v_mov_b32_e32 v45, v42
	v_mov_b32_e32 v42, v41
	v_mov_b32_e32 v44, v40
	v_pk_mul_f32 v[28:29], v[16:17], v[42:43]
	v_pk_mul_f32 v[40:41], v[24:25], v[42:43]
	v_mul_f32_e32 v30, v26, v36
	v_mul_f32_e32 v42, v18, v37
	v_mul_f32_e32 v36, v18, v36
	v_mov_b32_e32 v18, v27
	v_pk_fma_f32 v[20:21], v[20:21], v[52:53], v[54:55]
	v_pk_mul_f32 v[52:53], v[18:19], v[38:39]
	v_mul_f32_e32 v46, v26, v37
	v_mov_b32_e32 v31, v52
	v_mov_b32_e32 v43, v53
	v_pk_fma_f32 v[28:29], v[24:25], v[44:45], v[28:29] neg_lo:[0,0,1] neg_hi:[0,0,1]
	v_mov_b32_e32 v26, v19
	v_mov_b32_e32 v51, v60
	v_mov_b32_e32 v57, v61
	v_pk_add_f32 v[30:31], v[30:31], v[42:43] neg_lo:[0,1] neg_hi:[0,1]
	v_pk_mul_f32 v[18:19], v[26:27], v[38:39]
	v_mov_b64_e32 v[24:25], v[28:29]
	v_pk_add_f32 v[50:51], v[50:51], v[56:57] neg_lo:[0,1] neg_hi:[0,1]
	v_mov_b32_e32 v37, v18
	v_mov_b32_e32 v47, v19
	v_mov_b64_e32 v[26:27], v[30:31]
	v_mov_b64_e32 v[28:29], v[48:49]
	v_pk_fma_f32 v[16:17], v[16:17], v[44:45], v[40:41]
	v_pk_add_f32 v[18:19], v[36:37], v[46:47]
	v_mov_b64_e32 v[30:31], v[50:51]

;     __device__ __forceinline__ void operator()(const Acc& acc, const Unit& u, int wr, int wc, int fr, int fq) const {
;     ...
;                         const int pos = axis ? (t & 63) : (t >> 6);
;                         const f32x4* rp = (const f32x4*)(rope + pos * 16 + f0);
;                         const f32x4 c01 = rp[0], c23 = rp[1], c45 = rp[2], c67 = rp[3];
;                         f32x4 o0a, o0b, o1a, o1b;
;                         o0a[0] = x0a[0] * c01[0] - x1a[0] * c01[1]; o1a[0] = x1a[0] * c01[0] + x0a[0] * c01[1];
;                         o0a[1] = x0a[1] * c01[2] - x1a[1] * c01[3]; o1a[1] = x1a[1] * c01[2] + x0a[1] * c01[3];
;                         o0a[2] = x0a[2] * c23[0] - x1a[2] * c23[1]; o1a[2] = x1a[2] * c23[0] + x0a[2] * c23[1];
;                         o0a[3] = x0a[3] * c23[2] - x1a[3] * c23[3]; o1a[3] = x1a[3] * c23[2] + x0a[3] * c23[3];
;                         o0b[0] = x0b[0] * c45[0] - x1b[0] * c45[1]; o1b[0] = x1b[0] * c45[0] + x0b[0] * c45[1];
;                         o0b[1] = x0b[1] * c45[2] - x1b[1] * c45[3]; o1b[1] = x1b[1] * c45[2] + x0b[1] * c45[3];
;                         o0b[2] = x0b[2] * c67[0] - x1b[2] * c67[1]; o1b[2] = x1b[2] * c67[0] + x0b[2] * c67[1];
;                         o0b[3] = x0b[3] * c67[2] - x1b[3] * c67[3]; o1b[3] = x1b[3] * c67[2] + x0b[3] * c67[3];
;                         x0a = o0a; x0b = o0b; x1a = o1a; x1b = o1b;
.LBB0_626:
	s_and_saveexec_b64 s[8:9], s[14:15]
	s_cbranch_execz .LBB0_628
	v_and_b32_e32 v17, 63, v18
	v_lshrrev_b32_e32 v19, 6, v19
	v_cndmask_b32_e64 v17, v17, v19, s[0:1]
	v_lshlrev_b32_e32 v136, 7, v17
	v_lshl_add_u64 v[32:33], v[140:141], 0, v[136:137]
	v_add_u32_e32 v197, v196, v136
	ds_read_b128 v[20:23], v197 offset:48
	ds_read_b128 v[24:27], v197 offset:32
	ds_read_b128 v[28:31], v197 offset:16
	ds_read_b128 v[32:35], v197
	s_waitcnt lgkmcnt(0)
	v_mul_f32_e32 v40, v6, v29
	v_mov_b32_e32 v37, v34
	v_mov_b32_e32 v34, v33
	v_mov_b32_e32 v36, v32
	v_pk_mul_f32 v[32:33], v[4:5], v[34:35]
	v_pk_mul_f32 v[38:39], v[12:13], v[34:35]
	v_mul_f32_e32 v34, v14, v28
	v_mul_f32_e32 v28, v6, v28
	v_mul_f32_e32 v42, v14, v29
	v_mov_b32_e32 v6, v15
	v_mov_b32_e32 v14, v7
	v_pk_mul_f32 v[44:45], v[6:7], v[30:31]
	v_pk_mul_f32 v[6:7], v[14:15], v[30:31]
	v_pk_fma_f32 v[32:33], v[12:13], v[36:37], v[32:33] neg_lo:[0,0,1] neg_hi:[0,0,1]
	v_mov_b32_e32 v29, v6
	v_mov_b32_e32 v43, v7
	v_pk_add_f32 v[6:7], v[28:29], v[42:43]
	v_mov_b32_e32 v29, v26
	v_mov_b32_e32 v26, v25
	v_mov_b32_e32 v28, v24
	v_pk_mul_f32 v[12:13], v[0:1], v[26:27]
	v_pk_mul_f32 v[24:25], v[8:9], v[26:27]
	v_mul_f32_e32 v14, v10, v20
	v_mul_f32_e32 v26, v2, v21
	v_mul_f32_e32 v20, v2, v20
	v_mov_b32_e32 v2, v11
	v_pk_fma_f32 v[4:5], v[4:5], v[36:37], v[38:39]
	v_pk_mul_f32 v[36:37], v[2:3], v[22:23]
	v_mul_f32_e32 v30, v10, v21
	v_mov_b32_e32 v15, v36
	v_mov_b32_e32 v27, v37
	v_pk_fma_f32 v[12:13], v[8:9], v[28:29], v[12:13] neg_lo:[0,0,1] neg_hi:[0,0,1]
	v_mov_b32_e32 v10, v3
	v_mov_b32_e32 v35, v44
	v_mov_b32_e32 v41, v45
	v_pk_add_f32 v[14:15], v[14:15], v[26:27] neg_lo:[0,1] neg_hi:[0,1]
	v_pk_mul_f32 v[2:3], v[10:11], v[22:23]
	v_mov_b64_e32 v[8:9], v[12:13]
	v_pk_add_f32 v[34:35], v[34:35], v[40:41] neg_lo:[0,1] neg_hi:[0,1]
	v_mov_b32_e32 v21, v2
	v_mov_b32_e32 v31, v3
	v_mov_b64_e32 v[10:11], v[14:15]
	v_mov_b64_e32 v[12:13], v[32:33]
	v_pk_fma_f32 v[0:1], v[0:1], v[28:29], v[24:25]
	v_pk_add_f32 v[2:3], v[20:21], v[30:31]
	v_mov_b64_e32 v[14:15], v[34:35]
